# attention phase: workgroups >=128 run the B and C units first and the A units last, mixing the MFMA-dense A loop with low-power B/C code across the chip (same work per workgroup)
# speedup vs baseline: 1.0175x; 1.0175x over previous
.LBB0_473:
	v_writelane_b32 v252, s76, 29
	s_nop 1
	v_writelane_b32 v252, s77, 30
	s_or_b64 exec, exec, s[0:1]
	s_mov_b64 s[0:1], 0
	s_waitcnt lgkmcnt(0)
	s_barrier
	s_add_u32 s76, s96, s0
	s_addc_u32 s77, s97, s1
	v_readlane_b32 s0, v253, 34
	v_readlane_b32 s1, v253, 35
	s_andn2_b64 vcc, exec, s[0:1]
	s_cbranch_vccnz .LBB0_484
	s_mov_b32 s32, 0
	s_cmp_lt_u32 s52, 0x80
	s_cbranch_scc1 .Lat_A
	s_mov_b32 s32, 1
	s_branch .LBB0_484
.Lat_A:
	v_readlane_b32 s4, v252, 29
	s_lshl_b32 s90, s4, 6
	s_lshl_b32 s0, s4, 7
	s_add_u32 s10, s76, 0x2000000
	s_addc_u32 s11, s77, 0
	s_add_u32 s12, s76, 0x1000000
	s_addc_u32 s13, s77, 0
	s_lshl_b64 s[2:3], s[90:91], 2
	s_add_u32 s2, s76, s2
	s_addc_u32 s3, s77, s3
	v_readlane_b32 s5, v252, 30
	s_add_u32 s14, s2, 0x10adbb00
	s_mov_b32 s2, s4
	v_cvt_f32_u32_e32 v0, s4
	s_mov_b32 s5, s91
	s_addc_u32 s15, s3, 0
	v_writelane_b32 v252, s2, 29
	v_mul_f32_e32 v0, 0xbe99999a, v0
	v_mul_f32_e32 v0, 0x3fb8aa3b, v0
	v_writelane_b32 v252, s3, 30
	s_lshl_b64 s[2:3], s[4:5], 2
	s_add_u32 s2, s76, s2
	s_addc_u32 s3, s77, s3
	s_add_u32 s4, s2, 0x10ad8000
	s_addc_u32 s5, s3, 0
	v_exp_f32_e32 v0, v0
	s_add_u32 s16, s76, 0x9000000
	s_addc_u32 s17, s77, 0
	s_mov_b32 s1, s91
	s_add_u32 s18, s76, 0xd000000
	s_addc_u32 s19, s77, 0
	s_lshl_b64 s[0:1], s[0:1], 2
	v_readlane_b32 s20, v253, 0
	v_fmamk_f32 v0, v0, 0x3f19999a, v225
	v_readlane_b32 s21, v253, 1
	s_add_u32 s6, s20, s0
	v_add_f32_e32 v162, 1.0, v0
	s_addc_u32 s7, s21, s1
	v_readlane_b32 s20, v253, 61
	s_mov_b32 s21, s52
	v_readlane_b32 s22, v253, 2
	v_readlane_b32 s23, v253, 3
	v_readlane_b32 s24, v253, 4
	v_readlane_b32 s25, v253, 5
	v_readlane_b32 s26, v253, 6
	v_readlane_b32 s27, v253, 7
	s_branch .LBB0_476

.LBB0_484:
	s_cmp_eq_u32 s32, 2
	s_cbranch_scc1 .Lat_end
	v_readlane_b32 s0, v253, 36
	v_readlane_b32 s1, v253, 37
	s_andn2_b64 vcc, exec, s[0:1]
	s_cbranch_vccnz .LBB0_506
	s_add_u32 s0, s76, 0x7800000
	s_addc_u32 s1, s77, 0
	s_add_u32 s2, s76, 0x4800000
	s_addc_u32 s3, s77, 0
	s_add_u32 s16, s76, 0x3000000
	s_addc_u32 s17, s77, 0
	s_add_u32 s6, s76, 0x10900000
	s_addc_u32 s7, s77, 0
	s_mov_b32 s18, s52
	s_branch .LBB0_487

.LBB0_530:
	s_cmp_eq_u32 s32, 1
	s_cbranch_scc0 .Lat_end
	s_mov_b32 s32, 2
	s_branch .Lat_A
